# adds: prologue weight-transpose loads unrolled to 16 in flight; split row-max chain interleaved with PV MFMAs
# speedup vs baseline: 1.0036x; 1.0036x over previous
; DI unsigned pk2(float lo, float hi) { f32x2 v = {lo, hi}; bf16v2_t b = __builtin_convertvector(v, bf16v2_t); return __builtin_bit_cast(unsigned, b); }
; DI void wt_unit(const float* W, int K, int N, bf16_t* WT, int kt, int ntile, bool gu, float* scr  ) {
;     ...
;     const int n = tid & 127, kq = tid >> 7;
; #pragma unroll 4
;     for (int i = 0; i < 16; ++i) { const int k = kq * 16 + i; scr[k * 129 + n] = W[(size_t)(k0 + k) * N + n0 + n]; }
;   }
;   __syncthreads();
;   {
;     const int n = tid >> 2, kq = tid & 3;
;     const float* s = scr + (kq * 16) * 129 + n;
;     u32x4 o0, o1;
;     o0.x = pk2(s[0 * 129], s[1 * 129]); o0.y = pk2(s[2 * 129], s[3 * 129]); o0.z = pk2(s[4 * 129], s[5 * 129]); o0.w = pk2(s[6 * 129], s[7 * 129]);
;     o1.x = pk2(s[8 * 129], s[9 * 129]); o1.y = pk2(s[10 * 129], s[11 * 129]); o1.z = pk2(s[12 * 129], s[13 * 129]); o1.w = pk2(s[14 * 129], s[15 * 129]);
;     const int nsrc = n0 + n;
;     int ndst = nsrc;
;     if (gu) { const int sel = nsrc < FFH ? 0 : 1; const int j = nsrc - sel * FFH; ndst = (j >> 4) * 32 + sel * 16 + (j & 15); }
;     bf16_t* d = WT + (size_t)ndst * K + k0 + kq * 16;
;     *(u32x4*)d = o0; *(u32x4*)(d + 8) = o1;
.LBB0_41:
	v_or_b32_e32 v16, s25, v6
	s_add_i32 s36, s17, 2
	s_add_i32 s37, s25, 2
	s_add_i32 s38, s17, 4
	s_add_i32 s39, s25, 4
	s_add_i32 s42, s17, 6
	s_add_i32 s43, s25, 6
	v_or_b32_e32 v7, s17, v1
	v_add_u32_e32 v10, s12, v16
	v_or_b32_e32 v18, s36, v1
	v_or_b32_e32 v39, s37, v6
	v_or_b32_e32 v46, s38, v1
	v_or_b32_e32 v47, s39, v6
	v_or_b32_e32 v48, s42, v1
	v_or_b32_e32 v49, s43, v6
	v_add_u32_e32 v8, s16, v7
	v_ashrrev_i32_e32 v11, 31, v10
	v_add_u32_e32 v12, s16, v18
	v_add_u32_e32 v20, s12, v39
	v_add_u32_e32 v22, s16, v46
	v_add_u32_e32 v40, s12, v47
	v_add_u32_e32 v42, s16, v48
	v_add_u32_e32 v44, s12, v49
	v_ashrrev_i32_e32 v9, 31, v8
	v_lshlrev_b64 v[10:11], 12, v[10:11]
	v_ashrrev_i32_e32 v21, 31, v20
	v_ashrrev_i32_e32 v13, 31, v12
	v_ashrrev_i32_e32 v41, 31, v40
	v_ashrrev_i32_e32 v23, 31, v22
	v_ashrrev_i32_e32 v45, 31, v44
	v_ashrrev_i32_e32 v43, 31, v42
	v_lshlrev_b64 v[8:9], 12, v[8:9]
	v_lshl_add_u64 v[10:11], v[2:3], 0, v[10:11]
	v_lshlrev_b64 v[12:13], 12, v[12:13]
	v_lshlrev_b64 v[20:21], 12, v[20:21]
	v_lshlrev_b64 v[22:23], 12, v[22:23]
	v_lshlrev_b64 v[40:41], 12, v[40:41]
	v_lshlrev_b64 v[42:43], 12, v[42:43]
	v_lshlrev_b64 v[44:45], 12, v[44:45]
	v_lshl_add_u64 v[8:9], v[2:3], 0, v[8:9]
	v_lshl_add_u64 v[20:21], v[2:3], 0, v[20:21]
	v_lshl_add_u64 v[12:13], v[2:3], 0, v[12:13]
	v_lshl_add_u64 v[40:41], v[2:3], 0, v[40:41]
	v_lshl_add_u64 v[22:23], v[2:3], 0, v[22:23]
	v_lshl_add_u64 v[44:45], v[2:3], 0, v[44:45]
	v_lshl_add_u64 v[42:43], v[2:3], 0, v[42:43]
	global_load_dword v50, v[10:11], off
	global_load_dword v51, v[8:9], off
	global_load_dword v52, v[20:21], off
	global_load_dword v53, v[12:13], off
	global_load_dword v54, v[40:41], off
	global_load_dword v55, v[22:23], off
	global_load_dword v56, v[44:45], off
	global_load_dword v57, v[42:43], off
	s_add_i32 s25, s25, 8
	s_add_i32 s17, s17, 8
	s_add_i32 s26, s26, -8
	v_mad_u64_u32 v[108:109], s[36:37], v16, s48, v[4:5]
	s_cmp_lg_u32 s26, 0
	v_mad_u64_u32 v[110:111], s[36:37], v7, s48, v[4:5]
	v_mad_u64_u32 v[112:113], s[36:37], v39, s48, v[4:5]
	v_mad_u64_u32 v[114:115], s[36:37], v18, s48, v[4:5]
	v_mad_u64_u32 v[116:117], s[36:37], v47, s48, v[4:5]
	v_mad_u64_u32 v[118:119], s[36:37], v46, s48, v[4:5]
	v_mad_u64_u32 v[120:121], s[36:37], v49, s48, v[4:5]
	v_mad_u64_u32 v[122:123], s[36:37], v48, s48, v[4:5]
	v_or_b32_e32 v16, s25, v6
	s_add_i32 s36, s17, 2
	s_add_i32 s37, s25, 2
	s_add_i32 s38, s17, 4
	s_add_i32 s39, s25, 4
	s_add_i32 s42, s17, 6
	s_add_i32 s43, s25, 6
	v_or_b32_e32 v7, s17, v1
	v_add_u32_e32 v10, s12, v16
	v_or_b32_e32 v18, s36, v1
	v_or_b32_e32 v39, s37, v6
	v_or_b32_e32 v46, s38, v1
	v_or_b32_e32 v47, s39, v6
	v_or_b32_e32 v48, s42, v1
	v_or_b32_e32 v49, s43, v6
	v_add_u32_e32 v8, s16, v7
	v_ashrrev_i32_e32 v11, 31, v10
	v_add_u32_e32 v12, s16, v18
	v_add_u32_e32 v20, s12, v39
	v_add_u32_e32 v22, s16, v46
	v_add_u32_e32 v40, s12, v47
	v_add_u32_e32 v42, s16, v48
	v_add_u32_e32 v44, s12, v49
	v_ashrrev_i32_e32 v9, 31, v8
	v_lshlrev_b64 v[10:11], 12, v[10:11]
	v_ashrrev_i32_e32 v21, 31, v20
	v_ashrrev_i32_e32 v13, 31, v12
	v_ashrrev_i32_e32 v41, 31, v40
	v_ashrrev_i32_e32 v23, 31, v22
	v_ashrrev_i32_e32 v45, 31, v44
	v_ashrrev_i32_e32 v43, 31, v42
	v_lshlrev_b64 v[8:9], 12, v[8:9]
	v_lshl_add_u64 v[10:11], v[2:3], 0, v[10:11]
	v_lshlrev_b64 v[12:13], 12, v[12:13]
	v_lshlrev_b64 v[20:21], 12, v[20:21]
	v_lshlrev_b64 v[22:23], 12, v[22:23]
	v_lshlrev_b64 v[40:41], 12, v[40:41]
	v_lshlrev_b64 v[42:43], 12, v[42:43]
	v_lshlrev_b64 v[44:45], 12, v[44:45]
	v_lshl_add_u64 v[8:9], v[2:3], 0, v[8:9]
	v_lshl_add_u64 v[20:21], v[2:3], 0, v[20:21]
	v_lshl_add_u64 v[12:13], v[2:3], 0, v[12:13]
	v_lshl_add_u64 v[40:41], v[2:3], 0, v[40:41]
	v_lshl_add_u64 v[22:23], v[2:3], 0, v[22:23]
	v_lshl_add_u64 v[44:45], v[2:3], 0, v[44:45]
	v_lshl_add_u64 v[42:43], v[2:3], 0, v[42:43]
	global_load_dword v124, v[10:11], off
	global_load_dword v125, v[8:9], off
	global_load_dword v126, v[20:21], off
	global_load_dword v127, v[12:13], off
	global_load_dword v128, v[40:41], off
	global_load_dword v129, v[22:23], off
	global_load_dword v130, v[44:45], off
	global_load_dword v131, v[42:43], off
	s_add_i32 s25, s25, 8
	s_add_i32 s17, s17, 8
	s_add_i32 s26, s26, -8
	v_mad_u64_u32 v[8:9], s[36:37], v16, s48, v[4:5]
	s_cmp_lg_u32 s26, 0
	v_mad_u64_u32 v[10:11], s[36:37], v7, s48, v[4:5]
	v_mad_u64_u32 v[12:13], s[36:37], v39, s48, v[4:5]
	v_mad_u64_u32 v[20:21], s[36:37], v18, s48, v[4:5]
	v_mad_u64_u32 v[22:23], s[36:37], v47, s48, v[4:5]
	v_mad_u64_u32 v[40:41], s[36:37], v46, s48, v[4:5]
	v_mad_u64_u32 v[42:43], s[36:37], v49, s48, v[4:5]
	v_mad_u64_u32 v[44:45], s[36:37], v48, s48, v[4:5]
	s_waitcnt vmcnt(15)
	ds_write_b32 v108, v50
	s_waitcnt vmcnt(14)
	ds_write_b32 v110, v51
	s_waitcnt vmcnt(13)
	ds_write_b32 v112, v52
	s_waitcnt vmcnt(12)
	ds_write_b32 v114, v53
	s_waitcnt vmcnt(11)
	ds_write_b32 v116, v54
	s_waitcnt vmcnt(10)
	ds_write_b32 v118, v55
	s_waitcnt vmcnt(9)
	ds_write_b32 v120, v56
	s_waitcnt vmcnt(8)
	ds_write_b32 v122, v57
	s_waitcnt vmcnt(7)
	ds_write_b32 v8, v124
	s_waitcnt vmcnt(6)
	ds_write_b32 v10, v125
	s_waitcnt vmcnt(5)
	ds_write_b32 v12, v126
	s_waitcnt vmcnt(4)
	ds_write_b32 v20, v127
	s_waitcnt vmcnt(3)
	ds_write_b32 v22, v128
	s_waitcnt vmcnt(2)
	ds_write_b32 v40, v129
	s_waitcnt vmcnt(1)
	ds_write_b32 v42, v130
	s_waitcnt vmcnt(0)
	ds_write_b32 v44, v131
	v_lshlrev_b32_e32 v2, 4, v5
	v_and_b32_e32 v16, 48, v2
	v_mul_u32_u24_e32 v2, 0x204, v16
	v_and_b32_e32 v3, -4, v5
	v_add3_u32 v2, 0, v2, v3
	v_add_u32_e32 v3, 0x400, v2
	s_waitcnt lgkmcnt(0)
	s_barrier
	ds_read2_b32 v[10:11], v2 offset1:129
	ds_read2_b32 v[6:7], v3 offset0:2 offset1:131
	v_add_u32_e32 v3, 0x800, v2
	s_mul_i32 s16, s18, 0x580000
	ds_read2_b32 v[12:13], v3 offset0:4 offset1:133
	v_add_u32_e32 v3, 0xc00, v2
	s_add_u32 s14, s14, s16
	v_ashrrev_i32_e32 v1, 2, v5
	ds_read2_b32 v[8:9], v3 offset0:6 offset1:135
	v_add_u32_e32 v4, 0x1000, v2
	v_add_u32_e32 v5, 0x1400, v2
	v_add_u32_e32 v18, 0x1800, v2
	v_add_u32_e32 v2, 0x1c00, v2
	s_addc_u32 s15, s15, 0
	ds_read2_b32 v[2:3], v2 offset0:14 offset1:143
	ds_read2_b32 v[20:21], v18 offset0:12 offset1:141
	ds_read2_b32 v[22:23], v5 offset0:10 offset1:139
	ds_read2_b32 v[40:41], v4 offset0:8 offset1:137
	v_add_u32_e32 v1, s13, v1
	s_waitcnt lgkmcnt(6)
	v_cvt_pk_bf16_f32 v7, v6, v7
	v_cvt_pk_bf16_f32 v6, v10, v11
	v_mov_b64_e32 v[10:11], s[14:15]
	v_mad_i64_i32 v[10:11], s[14:15], v1, s67, v[10:11]
	s_mov_b32 s13, s27
	v_lshl_add_u64 v[10:11], s[12:13], 1, v[10:11]
	v_lshlrev_b32_e32 v16, 1, v16
	s_waitcnt lgkmcnt(4)
	v_cvt_pk_bf16_f32 v9, v8, v9
	v_cvt_pk_bf16_f32 v8, v12, v13
	v_lshl_add_u64 v[10:11], v[10:11], 0, v[16:17]
	s_waitcnt lgkmcnt(3)
	v_cvt_pk_bf16_f32 v5, v2, v3
	s_waitcnt lgkmcnt(2)
	v_cvt_pk_bf16_f32 v4, v20, v21
	s_waitcnt lgkmcnt(1)
	v_cvt_pk_bf16_f32 v3, v22, v23
	s_waitcnt lgkmcnt(0)
	v_cvt_pk_bf16_f32 v2, v40, v41
	global_store_dwordx4 v[10:11], v[6:9], off
	global_store_dwordx4 v[10:11], v[2:5], off offset:16
	s_mov_b64 s[12:13], 0

; DI unsigned pk2(float lo, float hi) { f32x2 v = {lo, hi}; bf16v2_t b = __builtin_convertvector(v, bf16v2_t); return __builtin_bit_cast(unsigned, b); }
; DI void wt_unit(const float* W, int K, int N, bf16_t* WT, int kt, int ntile, bool gu, float* scr  ) {
;     ...
;     const int n = tid & 127, kq = tid >> 7;
; #pragma unroll 4
;     for (int i = 0; i < 16; ++i) { const int k = kq * 16 + i; scr[k * 129 + n] = W[(size_t)(k0 + k) * N + n0 + n]; }
;   }
;   __syncthreads();
;   {
;     const int n = tid >> 2, kq = tid & 3;
;     const float* s = scr + (kq * 16) * 129 + n;
;     u32x4 o0, o1;
;     o0.x = pk2(s[0 * 129], s[1 * 129]); o0.y = pk2(s[2 * 129], s[3 * 129]); o0.z = pk2(s[4 * 129], s[5 * 129]); o0.w = pk2(s[6 * 129], s[7 * 129]);
;     o1.x = pk2(s[8 * 129], s[9 * 129]); o1.y = pk2(s[10 * 129], s[11 * 129]); o1.z = pk2(s[12 * 129], s[13 * 129]); o1.w = pk2(s[14 * 129], s[15 * 129]);
;     const int nsrc = n0 + n;
;     int ndst = nsrc;
;     if (gu) { const int sel = nsrc < FFH ? 0 : 1; const int j = nsrc - sel * FFH; ndst = (j >> 4) * 32 + sel * 16 + (j & 15); }
;     bf16_t* d = WT + (size_t)ndst * K + k0 + kq * 16;
;     *(u32x4*)d = o0; *(u32x4*)(d + 8) = o1;
.LBB0_45:
	v_or_b32_e32 v16, s25, v6
	s_add_i32 s36, s17, 2
	s_add_i32 s37, s25, 2
	s_add_i32 s38, s17, 4
	s_add_i32 s39, s25, 4
	s_add_i32 s42, s17, 6
	s_add_i32 s43, s25, 6
	v_or_b32_e32 v7, s17, v1
	v_add_u32_e32 v8, s14, v16
	v_or_b32_e32 v18, s36, v1
	v_or_b32_e32 v39, s37, v6
	v_or_b32_e32 v46, s38, v1
	v_or_b32_e32 v47, s39, v6
	v_or_b32_e32 v48, s42, v1
	v_or_b32_e32 v49, s43, v6
	v_add_u32_e32 v10, s16, v7
	v_mad_i64_i32 v[8:9], s[36:37], v8, s68, v[2:3]
	v_add_u32_e32 v20, s16, v18
	v_add_u32_e32 v12, s14, v39
	v_add_u32_e32 v40, s16, v46
	v_add_u32_e32 v22, s14, v47
	v_add_u32_e32 v44, s16, v48
	v_add_u32_e32 v42, s14, v49
	v_mad_i64_i32 v[10:11], s[36:37], v10, s68, v[2:3]
	v_mad_i64_i32 v[12:13], s[36:37], v12, s68, v[2:3]
	v_mad_i64_i32 v[20:21], s[36:37], v20, s68, v[2:3]
	v_mad_i64_i32 v[22:23], s[36:37], v22, s68, v[2:3]
	v_mad_i64_i32 v[40:41], s[36:37], v40, s68, v[2:3]
	v_mad_i64_i32 v[42:43], s[36:37], v42, s68, v[2:3]
	v_mad_i64_i32 v[44:45], s[36:37], v44, s68, v[2:3]
	global_load_dword v50, v[8:9], off
	global_load_dword v51, v[10:11], off
	global_load_dword v52, v[12:13], off
	global_load_dword v53, v[20:21], off
	global_load_dword v54, v[22:23], off
	global_load_dword v55, v[40:41], off
	global_load_dword v56, v[42:43], off
	global_load_dword v57, v[44:45], off
	s_add_i32 s25, s25, 8
	s_add_i32 s17, s17, 8
	s_add_i32 s26, s26, -8
	v_mad_u64_u32 v[108:109], s[36:37], v16, s48, v[4:5]
	s_cmp_lg_u32 s26, 0
	v_mad_u64_u32 v[110:111], s[36:37], v7, s48, v[4:5]
	v_mad_u64_u32 v[112:113], s[36:37], v39, s48, v[4:5]
	v_mad_u64_u32 v[114:115], s[36:37], v18, s48, v[4:5]
	v_mad_u64_u32 v[116:117], s[36:37], v47, s48, v[4:5]
	v_mad_u64_u32 v[118:119], s[36:37], v46, s48, v[4:5]
	v_mad_u64_u32 v[120:121], s[36:37], v49, s48, v[4:5]
	v_mad_u64_u32 v[122:123], s[36:37], v48, s48, v[4:5]
	v_or_b32_e32 v16, s25, v6
	s_add_i32 s36, s17, 2
	s_add_i32 s37, s25, 2
	s_add_i32 s38, s17, 4
	s_add_i32 s39, s25, 4
	s_add_i32 s42, s17, 6
	s_add_i32 s43, s25, 6
	v_or_b32_e32 v7, s17, v1
	v_add_u32_e32 v8, s14, v16
	v_or_b32_e32 v18, s36, v1
	v_or_b32_e32 v39, s37, v6
	v_or_b32_e32 v46, s38, v1
	v_or_b32_e32 v47, s39, v6
	v_or_b32_e32 v48, s42, v1
	v_or_b32_e32 v49, s43, v6
	v_add_u32_e32 v10, s16, v7
	v_mad_i64_i32 v[8:9], s[36:37], v8, s68, v[2:3]
	v_add_u32_e32 v20, s16, v18
	v_add_u32_e32 v12, s14, v39
	v_add_u32_e32 v40, s16, v46
	v_add_u32_e32 v22, s14, v47
	v_add_u32_e32 v44, s16, v48
	v_add_u32_e32 v42, s14, v49
	v_mad_i64_i32 v[10:11], s[36:37], v10, s68, v[2:3]
	v_mad_i64_i32 v[12:13], s[36:37], v12, s68, v[2:3]
	v_mad_i64_i32 v[20:21], s[36:37], v20, s68, v[2:3]
	v_mad_i64_i32 v[22:23], s[36:37], v22, s68, v[2:3]
	v_mad_i64_i32 v[40:41], s[36:37], v40, s68, v[2:3]
	v_mad_i64_i32 v[42:43], s[36:37], v42, s68, v[2:3]
	v_mad_i64_i32 v[44:45], s[36:37], v44, s68, v[2:3]
	global_load_dword v124, v[8:9], off
	global_load_dword v125, v[10:11], off
	global_load_dword v126, v[12:13], off
	global_load_dword v127, v[20:21], off
	global_load_dword v128, v[22:23], off
	global_load_dword v129, v[40:41], off
	global_load_dword v130, v[42:43], off
	global_load_dword v131, v[44:45], off
	s_add_i32 s25, s25, 8
	s_add_i32 s17, s17, 8
	s_add_i32 s26, s26, -8
	v_mad_u64_u32 v[8:9], s[36:37], v16, s48, v[4:5]
	s_cmp_lg_u32 s26, 0
	v_mad_u64_u32 v[10:11], s[36:37], v7, s48, v[4:5]
	v_mad_u64_u32 v[12:13], s[36:37], v39, s48, v[4:5]
	v_mad_u64_u32 v[20:21], s[36:37], v18, s48, v[4:5]
	v_mad_u64_u32 v[22:23], s[36:37], v47, s48, v[4:5]
	v_mad_u64_u32 v[40:41], s[36:37], v46, s48, v[4:5]
	v_mad_u64_u32 v[42:43], s[36:37], v49, s48, v[4:5]
	v_mad_u64_u32 v[44:45], s[36:37], v48, s48, v[4:5]
	s_waitcnt vmcnt(15)
	ds_write_b32 v108, v50
	s_waitcnt vmcnt(14)
	ds_write_b32 v110, v51
	s_waitcnt vmcnt(13)
	ds_write_b32 v112, v52
	s_waitcnt vmcnt(12)
	ds_write_b32 v114, v53
	s_waitcnt vmcnt(11)
	ds_write_b32 v116, v54
	s_waitcnt vmcnt(10)
	ds_write_b32 v118, v55
	s_waitcnt vmcnt(9)
	ds_write_b32 v120, v56
	s_waitcnt vmcnt(8)
	ds_write_b32 v122, v57
	s_waitcnt vmcnt(7)
	ds_write_b32 v8, v124
	s_waitcnt vmcnt(6)
	ds_write_b32 v10, v125
	s_waitcnt vmcnt(5)
	ds_write_b32 v12, v126
	s_waitcnt vmcnt(4)
	ds_write_b32 v20, v127
	s_waitcnt vmcnt(3)
	ds_write_b32 v22, v128
	s_waitcnt vmcnt(2)
	ds_write_b32 v40, v129
	s_waitcnt vmcnt(1)
	ds_write_b32 v42, v130
	s_waitcnt vmcnt(0)
	ds_write_b32 v44, v131
	s_mul_i32 s16, s18, 0xb00000
	v_lshlrev_b32_e32 v2, 4, v5
	s_add_u32 s12, s12, s16
	v_and_b32_e32 v16, 48, v2
	s_addc_u32 s13, s13, 0
	s_and_b32 s15, 0xffff, s15
	v_ashrrev_i32_e32 v1, 2, v5
	v_mul_u32_u24_e32 v2, 0x204, v16
	v_and_b32_e32 v3, -4, v5
	v_add3_u32 v4, 0, v2, v3
	v_add_u32_e32 v18, s15, v1
	v_add_u32_e32 v2, 0x400, v4
	v_cmp_lt_i32_e32 vcc, s69, v18
	s_waitcnt lgkmcnt(0)
	s_barrier
	ds_read2_b32 v[10:11], v4 offset1:129
	ds_read2_b32 v[6:7], v2 offset0:2 offset1:131
	v_add_u32_e32 v2, 0x800, v4
	v_cndmask_b32_e32 v39, 0, v37, vcc
	ds_read2_b32 v[12:13], v2 offset0:4 offset1:133
	v_add_u32_e32 v2, 0xc00, v4
	v_add_lshl_u32 v18, v39, v18, 1
	ds_read2_b32 v[8:9], v2 offset0:6 offset1:135
	v_add_u32_e32 v2, 0x1000, v4
	v_and_b32_e32 v18, 0xffffffe0, v18
	v_cndmask_b32_e64 v39, 0, 16, vcc
	v_and_b32_e32 v1, 15, v1
	ds_read2_b32 v[20:21], v2 offset0:8 offset1:137
	v_add_u32_e32 v2, 0x1400, v4
	v_add_u32_e32 v5, 0x1800, v4
	v_add_u32_e32 v4, 0x1c00, v4
	v_or3_b32 v40, v39, v1, v18
	ds_read2_b32 v[2:3], v2 offset0:10 offset1:139
	ds_read2_b32 v[22:23], v5 offset0:12 offset1:141
	ds_read2_b32 v[4:5], v4 offset0:14 offset1:143
	v_ashrrev_i32_e32 v41, 31, v40
	s_waitcnt lgkmcnt(6)
	v_cvt_pk_bf16_f32 v7, v6, v7
	v_cvt_pk_bf16_f32 v6, v10, v11
	v_lshlrev_b64 v[10:11], 11, v[40:41]
	v_lshl_add_u64 v[10:11], s[12:13], 0, v[10:11]
	s_lshl_b32 s26, s14, 1
	v_lshl_add_u64 v[10:11], v[10:11], 0, s[26:27]
	v_lshlrev_b32_e32 v16, 1, v16
	s_waitcnt lgkmcnt(4)
	v_cvt_pk_bf16_f32 v9, v8, v9
	v_cvt_pk_bf16_f32 v8, v12, v13
	v_lshl_add_u64 v[10:11], v[10:11], 0, v[16:17]
	s_waitcnt lgkmcnt(0)
	v_cvt_pk_bf16_f32 v5, v4, v5
	v_cvt_pk_bf16_f32 v4, v22, v23
	v_cvt_pk_bf16_f32 v3, v2, v3
	v_cvt_pk_bf16_f32 v2, v20, v21
	global_store_dwordx4 v[10:11], v[6:9], off
	global_store_dwordx4 v[10:11], v[2:5], off offset:16

; DI unsigned pk2(float lo, float hi) { f32x2 v = {lo, hi}; bf16v2_t b = __builtin_convertvector(v, bf16v2_t); return __builtin_bit_cast(unsigned, b); }
; DI void wt_unit(const float* W, int K, int N, bf16_t* WT, int kt, int ntile, bool gu, float* scr  ) {
;     ...
;     const int n = tid & 127, kq = tid >> 7;
; #pragma unroll 4
;     for (int i = 0; i < 16; ++i) { const int k = kq * 16 + i; scr[k * 129 + n] = W[(size_t)(k0 + k) * N + n0 + n]; }
;   }
;   __syncthreads();
;   {
;     const int n = tid >> 2, kq = tid & 3;
;     const float* s = scr + (kq * 16) * 129 + n;
;     u32x4 o0, o1;
;     o0.x = pk2(s[0 * 129], s[1 * 129]); o0.y = pk2(s[2 * 129], s[3 * 129]); o0.z = pk2(s[4 * 129], s[5 * 129]); o0.w = pk2(s[6 * 129], s[7 * 129]);
;     o1.x = pk2(s[8 * 129], s[9 * 129]); o1.y = pk2(s[10 * 129], s[11 * 129]); o1.z = pk2(s[12 * 129], s[13 * 129]); o1.w = pk2(s[14 * 129], s[15 * 129]);
;     const int nsrc = n0 + n;
;     int ndst = nsrc;
;     if (gu) { const int sel = nsrc < FFH ? 0 : 1; const int j = nsrc - sel * FFH; ndst = (j >> 4) * 32 + sel * 16 + (j & 15); }
;     bf16_t* d = WT + (size_t)ndst * K + k0 + kq * 16;
;     *(u32x4*)d = o0; *(u32x4*)(d + 8) = o1;
.LBB0_50:
	v_or_b32_e32 v16, s26, v6
	s_add_i32 s37, s25, 2
	s_add_i32 s38, s26, 2
	s_add_i32 s39, s25, 4
	s_add_i32 s42, s26, 4
	s_add_i32 s43, s25, 6
	s_add_i32 s44, s26, 6
	v_or_b32_e32 v7, s25, v1
	v_add_u32_e32 v10, s12, v16
	v_or_b32_e32 v18, s37, v1
	v_or_b32_e32 v39, s38, v6
	v_or_b32_e32 v46, s39, v1
	v_or_b32_e32 v47, s42, v6
	v_or_b32_e32 v48, s43, v1
	v_or_b32_e32 v49, s44, v6
	v_add_u32_e32 v8, s17, v7
	v_ashrrev_i32_e32 v11, 31, v10
	v_add_u32_e32 v12, s17, v18
	v_add_u32_e32 v20, s12, v39
	v_add_u32_e32 v22, s17, v46
	v_add_u32_e32 v40, s12, v47
	v_add_u32_e32 v42, s17, v48
	v_add_u32_e32 v44, s12, v49
	v_ashrrev_i32_e32 v9, 31, v8
	v_lshlrev_b64 v[10:11], 12, v[10:11]
	v_ashrrev_i32_e32 v21, 31, v20
	v_ashrrev_i32_e32 v13, 31, v12
	v_ashrrev_i32_e32 v41, 31, v40
	v_ashrrev_i32_e32 v23, 31, v22
	v_ashrrev_i32_e32 v45, 31, v44
	v_ashrrev_i32_e32 v43, 31, v42
	v_lshlrev_b64 v[8:9], 12, v[8:9]
	v_lshl_add_u64 v[10:11], v[2:3], 0, v[10:11]
	v_lshlrev_b64 v[12:13], 12, v[12:13]
	v_lshlrev_b64 v[20:21], 12, v[20:21]
	v_lshlrev_b64 v[22:23], 12, v[22:23]
	v_lshlrev_b64 v[40:41], 12, v[40:41]
	v_lshlrev_b64 v[42:43], 12, v[42:43]
	v_lshlrev_b64 v[44:45], 12, v[44:45]
	v_lshl_add_u64 v[8:9], v[2:3], 0, v[8:9]
	v_lshl_add_u64 v[20:21], v[2:3], 0, v[20:21]
	v_lshl_add_u64 v[12:13], v[2:3], 0, v[12:13]
	v_lshl_add_u64 v[40:41], v[2:3], 0, v[40:41]
	v_lshl_add_u64 v[22:23], v[2:3], 0, v[22:23]
	v_lshl_add_u64 v[44:45], v[2:3], 0, v[44:45]
	v_lshl_add_u64 v[42:43], v[2:3], 0, v[42:43]
	global_load_dword v50, v[10:11], off
	global_load_dword v51, v[8:9], off
	global_load_dword v52, v[20:21], off
	global_load_dword v53, v[12:13], off
	global_load_dword v54, v[40:41], off
	global_load_dword v55, v[22:23], off
	global_load_dword v56, v[44:45], off
	global_load_dword v57, v[42:43], off
	s_add_i32 s26, s26, 8
	s_add_i32 s25, s25, 8
	s_add_i32 s36, s36, -8
	v_mad_u64_u32 v[108:109], s[38:39], v16, s48, v[4:5]
	s_cmp_lg_u32 s36, 0
	v_mad_u64_u32 v[110:111], s[38:39], v7, s48, v[4:5]
	v_mad_u64_u32 v[112:113], s[38:39], v39, s48, v[4:5]
	v_mad_u64_u32 v[114:115], s[38:39], v18, s48, v[4:5]
	v_mad_u64_u32 v[116:117], s[38:39], v47, s48, v[4:5]
	v_mad_u64_u32 v[118:119], s[38:39], v46, s48, v[4:5]
	v_mad_u64_u32 v[120:121], s[38:39], v49, s48, v[4:5]
	v_mad_u64_u32 v[122:123], s[38:39], v48, s48, v[4:5]
	v_or_b32_e32 v16, s26, v6
	s_add_i32 s37, s25, 2
	s_add_i32 s38, s26, 2
	s_add_i32 s39, s25, 4
	s_add_i32 s42, s26, 4
	s_add_i32 s43, s25, 6
	s_add_i32 s44, s26, 6
	v_or_b32_e32 v7, s25, v1
	v_add_u32_e32 v10, s12, v16
	v_or_b32_e32 v18, s37, v1
	v_or_b32_e32 v39, s38, v6
	v_or_b32_e32 v46, s39, v1
	v_or_b32_e32 v47, s42, v6
	v_or_b32_e32 v48, s43, v1
	v_or_b32_e32 v49, s44, v6
	v_add_u32_e32 v8, s17, v7
	v_ashrrev_i32_e32 v11, 31, v10
	v_add_u32_e32 v12, s17, v18
	v_add_u32_e32 v20, s12, v39
	v_add_u32_e32 v22, s17, v46
	v_add_u32_e32 v40, s12, v47
	v_add_u32_e32 v42, s17, v48
	v_add_u32_e32 v44, s12, v49
	v_ashrrev_i32_e32 v9, 31, v8
	v_lshlrev_b64 v[10:11], 12, v[10:11]
	v_ashrrev_i32_e32 v21, 31, v20
	v_ashrrev_i32_e32 v13, 31, v12
	v_ashrrev_i32_e32 v41, 31, v40
	v_ashrrev_i32_e32 v23, 31, v22
	v_ashrrev_i32_e32 v45, 31, v44
	v_ashrrev_i32_e32 v43, 31, v42
	v_lshlrev_b64 v[8:9], 12, v[8:9]
	v_lshl_add_u64 v[10:11], v[2:3], 0, v[10:11]
	v_lshlrev_b64 v[12:13], 12, v[12:13]
	v_lshlrev_b64 v[20:21], 12, v[20:21]
	v_lshlrev_b64 v[22:23], 12, v[22:23]
	v_lshlrev_b64 v[40:41], 12, v[40:41]
	v_lshlrev_b64 v[42:43], 12, v[42:43]
	v_lshlrev_b64 v[44:45], 12, v[44:45]
	v_lshl_add_u64 v[8:9], v[2:3], 0, v[8:9]
	v_lshl_add_u64 v[20:21], v[2:3], 0, v[20:21]
	v_lshl_add_u64 v[12:13], v[2:3], 0, v[12:13]
	v_lshl_add_u64 v[40:41], v[2:3], 0, v[40:41]
	v_lshl_add_u64 v[22:23], v[2:3], 0, v[22:23]
	v_lshl_add_u64 v[44:45], v[2:3], 0, v[44:45]
	v_lshl_add_u64 v[42:43], v[2:3], 0, v[42:43]
	global_load_dword v124, v[10:11], off
	global_load_dword v125, v[8:9], off
	global_load_dword v126, v[20:21], off
	global_load_dword v127, v[12:13], off
	global_load_dword v128, v[40:41], off
	global_load_dword v129, v[22:23], off
	global_load_dword v130, v[44:45], off
	global_load_dword v131, v[42:43], off
	s_add_i32 s26, s26, 8
	s_add_i32 s25, s25, 8
	s_add_i32 s36, s36, -8
	v_mad_u64_u32 v[8:9], s[38:39], v16, s48, v[4:5]
	s_cmp_lg_u32 s36, 0
	v_mad_u64_u32 v[10:11], s[38:39], v7, s48, v[4:5]
	v_mad_u64_u32 v[12:13], s[38:39], v39, s48, v[4:5]
	v_mad_u64_u32 v[20:21], s[38:39], v18, s48, v[4:5]
	v_mad_u64_u32 v[22:23], s[38:39], v47, s48, v[4:5]
	v_mad_u64_u32 v[40:41], s[38:39], v46, s48, v[4:5]
	v_mad_u64_u32 v[42:43], s[38:39], v49, s48, v[4:5]
	v_mad_u64_u32 v[44:45], s[38:39], v48, s48, v[4:5]
	s_waitcnt vmcnt(15)
	ds_write_b32 v108, v50
	s_waitcnt vmcnt(14)
	ds_write_b32 v110, v51
	s_waitcnt vmcnt(13)
	ds_write_b32 v112, v52
	s_waitcnt vmcnt(12)
	ds_write_b32 v114, v53
	s_waitcnt vmcnt(11)
	ds_write_b32 v116, v54
	s_waitcnt vmcnt(10)
	ds_write_b32 v118, v55
	s_waitcnt vmcnt(9)
	ds_write_b32 v120, v56
	s_waitcnt vmcnt(8)
	ds_write_b32 v122, v57
	s_waitcnt vmcnt(7)
	ds_write_b32 v8, v124
	s_waitcnt vmcnt(6)
	ds_write_b32 v10, v125
	s_waitcnt vmcnt(5)
	ds_write_b32 v12, v126
	s_waitcnt vmcnt(4)
	ds_write_b32 v20, v127
	s_waitcnt vmcnt(3)
	ds_write_b32 v22, v128
	s_waitcnt vmcnt(2)
	ds_write_b32 v40, v129
	s_waitcnt vmcnt(1)
	ds_write_b32 v42, v130
	s_waitcnt vmcnt(0)
	ds_write_b32 v44, v131
	v_lshlrev_b32_e32 v2, 4, v5
	v_and_b32_e32 v16, 48, v2
	v_mul_u32_u24_e32 v2, 0x204, v16
	v_and_b32_e32 v3, -4, v5
	v_add3_u32 v2, 0, v2, v3
	v_add_u32_e32 v3, 0x400, v2
	s_waitcnt lgkmcnt(0)
	s_barrier
	ds_read2_b32 v[10:11], v2 offset1:129
	ds_read2_b32 v[6:7], v3 offset0:2 offset1:131
	v_add_u32_e32 v3, 0x800, v2
	v_ashrrev_i32_e32 v1, 2, v5
	ds_read2_b32 v[12:13], v3 offset0:4 offset1:133
	v_add_u32_e32 v3, 0xc00, v2
	s_lshl_b32 s16, s16, 1
	ds_read2_b32 v[8:9], v3 offset0:6 offset1:135
	v_add_u32_e32 v4, 0x1000, v2
	v_add_u32_e32 v5, 0x1400, v2
	v_add_u32_e32 v18, 0x1800, v2
	v_add_u32_e32 v2, 0x1c00, v2
	v_add_u32_e32 v42, s13, v1
	s_add_u32 s14, s14, s16
	ds_read2_b32 v[2:3], v2 offset0:14 offset1:143
	ds_read2_b32 v[20:21], v18 offset0:12 offset1:141
	ds_read2_b32 v[22:23], v5 offset0:10 offset1:139
	ds_read2_b32 v[40:41], v4 offset0:8 offset1:137
	v_ashrrev_i32_e32 v43, 31, v42
	s_addc_u32 s15, s15, 0
	s_waitcnt lgkmcnt(6)
	v_cvt_pk_bf16_f32 v7, v6, v7
	v_cvt_pk_bf16_f32 v6, v10, v11
	v_lshlrev_b64 v[10:11], 11, v[42:43]
	v_lshl_add_u64 v[10:11], s[14:15], 0, v[10:11]
	s_mov_b32 s13, s27
	v_lshl_add_u64 v[10:11], s[12:13], 1, v[10:11]
	v_lshlrev_b32_e32 v16, 1, v16
	s_waitcnt lgkmcnt(4)
	v_cvt_pk_bf16_f32 v9, v8, v9
	v_cvt_pk_bf16_f32 v8, v12, v13
	v_lshl_add_u64 v[10:11], v[10:11], 0, v[16:17]
	s_waitcnt lgkmcnt(3)
	v_cvt_pk_bf16_f32 v5, v2, v3
	s_waitcnt lgkmcnt(2)
	v_cvt_pk_bf16_f32 v4, v20, v21
	s_waitcnt lgkmcnt(1)
	v_cvt_pk_bf16_f32 v3, v22, v23
	s_waitcnt lgkmcnt(0)
	v_cvt_pk_bf16_f32 v2, v40, v41
	global_store_dwordx4 v[10:11], v[6:9], off
	global_store_dwordx4 v[10:11], v[2:5], off offset:16

; DI unsigned pk2(float lo, float hi) { f32x2 v = {lo, hi}; bf16v2_t b = __builtin_convertvector(v, bf16v2_t); return __builtin_bit_cast(unsigned, b); }
; DI void wt_unit(const float* W, int K, int N, bf16_t* WT, int kt, int ntile, bool gu, float* scr  ) {
;     ...
;     const int n = tid & 127, kq = tid >> 7;
; #pragma unroll 4
;     for (int i = 0; i < 16; ++i) { const int k = kq * 16 + i; scr[k * 129 + n] = W[(size_t)(k0 + k) * N + n0 + n]; }
;   }
;   __syncthreads();
;   {
;     const int n = tid >> 2, kq = tid & 3;
;     const float* s = scr + (kq * 16) * 129 + n;
;     u32x4 o0, o1;
;     o0.x = pk2(s[0 * 129], s[1 * 129]); o0.y = pk2(s[2 * 129], s[3 * 129]); o0.z = pk2(s[4 * 129], s[5 * 129]); o0.w = pk2(s[6 * 129], s[7 * 129]);
;     o1.x = pk2(s[8 * 129], s[9 * 129]); o1.y = pk2(s[10 * 129], s[11 * 129]); o1.z = pk2(s[12 * 129], s[13 * 129]); o1.w = pk2(s[14 * 129], s[15 * 129]);
;     const int nsrc = n0 + n;
;     int ndst = nsrc;
;     if (gu) { const int sel = nsrc < FFH ? 0 : 1; const int j = nsrc - sel * FFH; ndst = (j >> 4) * 32 + sel * 16 + (j & 15); }
;     bf16_t* d = WT + (size_t)ndst * K + k0 + kq * 16;
;     *(u32x4*)d = o0; *(u32x4*)(d + 8) = o1;
.LBB0_55:
	v_or_b32_e32 v16, s25, v6
	s_add_i32 s26, s19, 2
	s_add_i32 s36, s25, 2
	s_add_i32 s37, s19, 4
	s_add_i32 s38, s25, 4
	s_add_i32 s39, s19, 6
	s_add_i32 s42, s25, 6
	v_or_b32_e32 v7, s19, v1
	v_add_u32_e32 v8, s12, v16
	v_or_b32_e32 v18, s26, v1
	v_or_b32_e32 v39, s36, v6
	v_or_b32_e32 v46, s37, v1
	v_or_b32_e32 v47, s38, v6
	v_or_b32_e32 v48, s39, v1
	v_or_b32_e32 v49, s42, v6
	v_add_u32_e32 v10, s15, v7
	v_mad_i64_i32 v[8:9], s[36:37], v8, s70, v[2:3]
	v_add_u32_e32 v20, s15, v18
	v_add_u32_e32 v12, s12, v39
	v_add_u32_e32 v40, s15, v46
	v_add_u32_e32 v22, s12, v47
	v_add_u32_e32 v44, s15, v48
	v_add_u32_e32 v42, s12, v49
	v_mad_i64_i32 v[10:11], s[36:37], v10, s70, v[2:3]
	v_mad_i64_i32 v[12:13], s[36:37], v12, s70, v[2:3]
	v_mad_i64_i32 v[20:21], s[36:37], v20, s70, v[2:3]
	v_mad_i64_i32 v[22:23], s[36:37], v22, s70, v[2:3]
	v_mad_i64_i32 v[40:41], s[36:37], v40, s70, v[2:3]
	v_mad_i64_i32 v[42:43], s[36:37], v42, s70, v[2:3]
	v_mad_i64_i32 v[44:45], s[36:37], v44, s70, v[2:3]
	global_load_dword v50, v[8:9], off
	global_load_dword v51, v[10:11], off
	global_load_dword v52, v[12:13], off
	global_load_dword v53, v[20:21], off
	global_load_dword v54, v[22:23], off
	global_load_dword v55, v[40:41], off
	global_load_dword v56, v[42:43], off
	global_load_dword v57, v[44:45], off
	s_add_i32 s25, s25, 8
	s_add_i32 s19, s19, 8
	s_add_i32 s13, s13, -8
	v_mad_u64_u32 v[108:109], s[36:37], v16, s48, v[4:5]
	s_cmp_lg_u32 s13, 0
	v_mad_u64_u32 v[110:111], s[36:37], v7, s48, v[4:5]
	v_mad_u64_u32 v[112:113], s[36:37], v39, s48, v[4:5]
	v_mad_u64_u32 v[114:115], s[36:37], v18, s48, v[4:5]
	v_mad_u64_u32 v[116:117], s[36:37], v47, s48, v[4:5]
	v_mad_u64_u32 v[118:119], s[36:37], v46, s48, v[4:5]
	v_mad_u64_u32 v[120:121], s[36:37], v49, s48, v[4:5]
	v_mad_u64_u32 v[122:123], s[36:37], v48, s48, v[4:5]
	v_or_b32_e32 v16, s25, v6
	s_add_i32 s26, s19, 2
	s_add_i32 s36, s25, 2
	s_add_i32 s37, s19, 4
	s_add_i32 s38, s25, 4
	s_add_i32 s39, s19, 6
	s_add_i32 s42, s25, 6
	v_or_b32_e32 v7, s19, v1
	v_add_u32_e32 v8, s12, v16
	v_or_b32_e32 v18, s26, v1
	v_or_b32_e32 v39, s36, v6
	v_or_b32_e32 v46, s37, v1
	v_or_b32_e32 v47, s38, v6
	v_or_b32_e32 v48, s39, v1
	v_or_b32_e32 v49, s42, v6
	v_add_u32_e32 v10, s15, v7
	v_mad_i64_i32 v[8:9], s[36:37], v8, s70, v[2:3]
	v_add_u32_e32 v20, s15, v18
	v_add_u32_e32 v12, s12, v39
	v_add_u32_e32 v40, s15, v46
	v_add_u32_e32 v22, s12, v47
	v_add_u32_e32 v44, s15, v48
	v_add_u32_e32 v42, s12, v49
	v_mad_i64_i32 v[10:11], s[36:37], v10, s70, v[2:3]
	v_mad_i64_i32 v[12:13], s[36:37], v12, s70, v[2:3]
	v_mad_i64_i32 v[20:21], s[36:37], v20, s70, v[2:3]
	v_mad_i64_i32 v[22:23], s[36:37], v22, s70, v[2:3]
	v_mad_i64_i32 v[40:41], s[36:37], v40, s70, v[2:3]
	v_mad_i64_i32 v[42:43], s[36:37], v42, s70, v[2:3]
	v_mad_i64_i32 v[44:45], s[36:37], v44, s70, v[2:3]
	global_load_dword v124, v[8:9], off
	global_load_dword v125, v[10:11], off
	global_load_dword v126, v[12:13], off
	global_load_dword v127, v[20:21], off
	global_load_dword v128, v[22:23], off
	global_load_dword v129, v[40:41], off
	global_load_dword v130, v[42:43], off
	global_load_dword v131, v[44:45], off
	s_add_i32 s25, s25, 8
	s_add_i32 s19, s19, 8
	s_add_i32 s13, s13, -8
	v_mad_u64_u32 v[8:9], s[36:37], v16, s48, v[4:5]
	s_cmp_lg_u32 s13, 0
	v_mad_u64_u32 v[10:11], s[36:37], v7, s48, v[4:5]
	v_mad_u64_u32 v[12:13], s[36:37], v39, s48, v[4:5]
	v_mad_u64_u32 v[20:21], s[36:37], v18, s48, v[4:5]
	v_mad_u64_u32 v[22:23], s[36:37], v47, s48, v[4:5]
	v_mad_u64_u32 v[40:41], s[36:37], v46, s48, v[4:5]
	v_mad_u64_u32 v[42:43], s[36:37], v49, s48, v[4:5]
	v_mad_u64_u32 v[44:45], s[36:37], v48, s48, v[4:5]
	s_waitcnt vmcnt(15)
	ds_write_b32 v108, v50
	s_waitcnt vmcnt(14)
	ds_write_b32 v110, v51
	s_waitcnt vmcnt(13)
	ds_write_b32 v112, v52
	s_waitcnt vmcnt(12)
	ds_write_b32 v114, v53
	s_waitcnt vmcnt(11)
	ds_write_b32 v116, v54
	s_waitcnt vmcnt(10)
	ds_write_b32 v118, v55
	s_waitcnt vmcnt(9)
	ds_write_b32 v120, v56
	s_waitcnt vmcnt(8)
	ds_write_b32 v122, v57
	s_waitcnt vmcnt(7)
	ds_write_b32 v8, v124
	s_waitcnt vmcnt(6)
	ds_write_b32 v10, v125
	s_waitcnt vmcnt(5)
	ds_write_b32 v12, v126
	s_waitcnt vmcnt(4)
	ds_write_b32 v20, v127
	s_waitcnt vmcnt(3)
	ds_write_b32 v22, v128
	s_waitcnt vmcnt(2)
	ds_write_b32 v40, v129
	s_waitcnt vmcnt(1)
	ds_write_b32 v42, v130
	s_waitcnt vmcnt(0)
	ds_write_b32 v44, v131
	v_lshlrev_b32_e32 v2, 4, v5
	v_and_b32_e32 v16, 48, v2
	v_mul_u32_u24_e32 v2, 0x204, v16
	v_and_b32_e32 v3, -4, v5
	v_add3_u32 v2, 0, v2, v3
	v_add_u32_e32 v3, 0x400, v2
	s_waitcnt lgkmcnt(0)
	s_barrier
	ds_read2_b32 v[10:11], v2 offset1:129
	ds_read2_b32 v[6:7], v3 offset0:2 offset1:131
	v_add_u32_e32 v3, 0x800, v2
	v_ashrrev_i32_e32 v1, 2, v5
	ds_read2_b32 v[12:13], v3 offset0:4 offset1:133
	v_add_u32_e32 v3, 0xc00, v2
	s_mul_i32 s18, s18, 0x580000
	ds_read2_b32 v[8:9], v3 offset0:6 offset1:135
	v_add_u32_e32 v4, 0x1000, v2
	v_add_u32_e32 v5, 0x1400, v2
	v_add_u32_e32 v18, 0x1800, v2
	v_add_u32_e32 v2, 0x1c00, v2
	v_add_u32_e32 v42, s14, v1
	s_add_u32 s16, s16, s18
	ds_read2_b32 v[2:3], v2 offset0:14 offset1:143
	ds_read2_b32 v[20:21], v18 offset0:12 offset1:141
	ds_read2_b32 v[22:23], v5 offset0:10 offset1:139
	ds_read2_b32 v[40:41], v4 offset0:8 offset1:137
	v_ashrrev_i32_e32 v43, 31, v42
	s_addc_u32 s17, s17, 0
	s_waitcnt lgkmcnt(6)
	v_cvt_pk_bf16_f32 v7, v6, v7
	v_cvt_pk_bf16_f32 v6, v10, v11
	v_lshlrev_b64 v[10:11], 11, v[42:43]
	v_lshl_add_u64 v[10:11], s[16:17], 0, v[10:11]
	s_ashr_i32 s13, s12, 31
	v_lshl_add_u64 v[10:11], s[12:13], 1, v[10:11]
	v_lshlrev_b32_e32 v16, 1, v16
	s_waitcnt lgkmcnt(4)
	v_cvt_pk_bf16_f32 v9, v8, v9
	v_cvt_pk_bf16_f32 v8, v12, v13
	v_lshl_add_u64 v[10:11], v[10:11], 0, v[16:17]
	s_waitcnt lgkmcnt(3)
	v_cvt_pk_bf16_f32 v5, v2, v3
	s_waitcnt lgkmcnt(2)
	v_cvt_pk_bf16_f32 v4, v20, v21
	s_waitcnt lgkmcnt(1)
	v_cvt_pk_bf16_f32 v3, v22, v23
	s_waitcnt lgkmcnt(0)
	v_cvt_pk_bf16_f32 v2, v40, v41
	global_store_dwordx4 v[10:11], v[6:9], off
	global_store_dwordx4 v[10:11], v[2:5], off offset:16

; #define MFMA32(a, b, c) __builtin_amdgcn_mfma_f32_32x32x16_bf16((a), (b), (c), 0, 0, 0)
; #define VLOAD(dst, sbv, q) do { _Pragma("unroll") for (int d_ = 0; d_ < 4; ++d_) dst[d_] = *(const lds_bf16x8*)((sbv) + vo[q] + d_ * 4096); } while (0)
; #define FENCE __builtin_amdgcn_sched_barrier(0)
; DI void diff_unit(KP p, int l, int b, int h, int qb, int isctx, float lamv, float lam_init, char* ldsc) {
;     ...
;   for (int kt = 0; kt < nt - 1; ++kt) {
;     asm volatile("s_waitcnt vmcnt(0)" ::: "memory");
;     __builtin_amdgcn_s_barrier();
;     const int stg1 = stg == 2 ? 0 : stg + 1;
;     if (kt + 2 < nt) { const int s2_ = stg >= 1 ? stg - 1 : 2; DISSUE(kt + 2, s2_); }
;     if (need) {
; #pragma unroll
;       for (int d = 0; d < 4; ++d) o[d] *= alpha;
;     }
;     const lds_u8* sbv = L + stg * STG + 16384;
;     const lds_u8* sbk = L + stg1 * STG + comp * 8192;
;     bf16x8 kf[2][4];
;     f32x16 st[2];
; #pragma unroll
;     for (int t = 0; t < 2; ++t)
; #pragma unroll
;       for (int ks = 0; ks < 4; ++ks) kf[t][ks] = *(const lds_bf16x8*)(sbk + ko[ks] + t * 4096);
;     FENCE;
;     pv_grp(o, vA, P[0]); pv_grp(o, vB, P[1]);
;     VLOAD(vA, sbv, 2); VLOAD(vB, sbv, 3);
;     FENCE;
; #pragma unroll
;     for (int i = 0; i < 16; ++i) { st[0][i] = 0.f; st[1][i] = 0.f; }
; #pragma unroll
;     for (int ks = 0; ks < 4; ++ks) st[0] = MFMA32(kf[0][ks], qf[ks], st[0]);
; #pragma unroll
;     for (int ks = 0; ks < 4; ++ks) st[1] = MFMA32(kf[1][ks], qf[ks], st[1]);
;     FENCE;
.LBB0_477:
	s_add_i32 s2, s17, 1
	s_and_b32 s16, s2, 3
	s_lshl_b32 s2, s16, 15
	s_add_i32 s15, s2, 0
	s_add_i32 s2, s15, s14
	v_add_u32_e32 v0, s2, v141
	v_add_u32_e32 v140, s2, v145
	v_add_u32_e32 v191, s2, v147
	v_add_u32_e32 v216, s2, v148
	ds_read_b128 v[154:157], v0
	ds_read_b128 v[192:195], v0 offset:4096
	ds_read_b128 v[196:199], v140
	ds_read_b128 v[200:203], v140 offset:4096
	ds_read_b128 v[204:207], v191
	ds_read_b128 v[208:211], v191 offset:4096
	ds_read_b128 v[212:215], v216
	ds_read_b128 v[216:219], v216 offset:4096
	s_lshl_b32 s2, s17, 15
	s_add_i32 s2, s2, 0
	s_waitcnt lgkmcnt(8)
	v_mfma_f32_32x32x16_bf16 v[50:65], v[86:89], v[66:69], v[50:65]
	v_add_u32_e32 v0, s2, v149
	ds_read_b128 v[220:223], v0 offset:24576
	ds_read_b128 v[224:227], v0 offset:28672
	s_add_i32 s18, s3, 0xc0
	s_add_i32 s19, s10, 64
	s_cmp_eq_u32 s11, 0
	s_cselect_b32 s19, s18, s19
	s_add_i32 s18, s17, 3
	s_and_b32 s18, s18, 3
	s_lshl_b32 s18, s18, 15
	s_add_i32 s18, s13, s18
	v_mad_i64_i32 v[244:245], vcc, s19, v185, v[136:137]
	v_lshl_add_u64 v[246:247], v[244:245], 0, s[96:97]
	v_lshl_add_u64 v[244:245], v[244:245], 0, s[52:53]
	v_lshl_add_u64 v[248:249], v[138:139], 0, s[60:61]
	s_mov_b32 m0, s18
	v_mfma_f32_32x32x16_bf16 v[34:49], v[82:85], v[66:69], v[34:49]
	global_load_lds_dwordx4 v[246:247], off
	s_add_i32 m0, s18, 0x2000
	v_mfma_f32_32x32x16_bf16 v[18:33], v[78:81], v[66:69], v[18:33]
	v_mfma_f32_32x32x16_bf16 v[2:17], v[74:77], v[66:69], v[2:17]
	global_load_lds_dwordx4 v[244:245], off
	s_add_i32 m0, s18, 0x4000
	v_mfma_f32_32x32x16_bf16 v[50:65], v[126:129], v[70:73], v[50:65]
	ds_read_b128 v[126:129], v0 offset:20480
	v_mfma_f32_32x32x16_bf16 v[34:49], v[122:125], v[70:73], v[34:49]
	ds_read_b128 v[122:125], v0 offset:16384
	v_add_u32_e32 v0, s2, v146
	ds_read_b128 v[228:231], v0 offset:16384
	ds_read_b128 v[232:235], v0 offset:20480
	ds_read_b128 v[236:239], v0 offset:24576
	ds_read_b128 v[240:243], v0 offset:28672
	v_mfma_f32_32x32x16_bf16 v[18:33], v[94:97], v[70:73], v[18:33]
	v_mfma_f32_32x32x16_bf16 v[2:17], v[90:93], v[70:73], v[2:17]
	global_load_lds_dwordx4 v[248:249], off
	s_add_i32 m0, s18, 0x6000
	s_waitcnt lgkmcnt(8)
	v_mfma_f32_32x32x16_bf16 v[66:81], v[192:195], v[98:101], 0
	v_mfma_f32_32x32x16_bf16 v[82:97], v[154:157], v[98:101], 0
	v_mfma_f32_32x32x16_bf16 v[66:81], v[200:203], v[102:105], v[66:81]
	v_mfma_f32_32x32x16_bf16 v[82:97], v[196:199], v[102:105], v[82:97]
	global_load_lds_dwordx4 v[138:139], off
	v_mfma_f32_32x32x16_bf16 v[66:81], v[208:211], v[106:109], v[66:81]
	v_mfma_f32_32x32x16_bf16 v[82:97], v[204:207], v[106:109], v[82:97]
	v_mfma_f32_32x32x16_bf16 v[66:81], v[216:219], v[110:113], v[66:81]
	v_mfma_f32_32x32x16_bf16 v[82:97], v[212:215], v[110:113], v[82:97]
	s_waitcnt lgkmcnt(0)
; #define FENCE __builtin_amdgcn_sched_barrier(0)
; DI void diff_unit(KP p, int l, int b, int h, int qb, int isctx, float lamv, float lam_init, char* ldsc) {
;     ...
;     pv_grp(o, vA, P[2]);
;     const float mx = tile_max(st);
;     need = !__all(mx <= m + 8.0f);
;     const float mn = need ? fmaxf(m, mx) : m;
;     alpha = __builtin_amdgcn_exp2f(m - mn);
;     FENCE;
;     float ps = exp_pack1<0>(st, mn, P[0]);
;     ps += exp_pack1<1>(st, mn, P[1]);
;     ps += exp_pack1<2>(st, mn, P[2]);
;     pv_grp(o, vB, P[3]);
;     ps += exp_pack1<3>(st, mn, P[3]);
; #pragma unroll
;     for (int q = 0; q < 4; ++q) { __builtin_amdgcn_sched_group_barrier(0x402, 18, 0); __builtin_amdgcn_sched_group_barrier(0x008, 1, 0); }
;     lsum = lsum * alpha + ps; m = mn;
	v_mfma_f32_32x32x16_bf16 v[50:65], v[122:125], v[118:121], v[50:65]
	s_nop 9
	v_max3_f32 v0, v82, v83, v84
	v_max3_f32 v250, v66, v67, v68
	v_mfma_f32_32x32x16_bf16 v[34:49], v[126:129], v[118:121], v[34:49]
	v_max3_f32 v0, v0, v85, v86
	v_max3_f32 v250, v250, v69, v70
	v_max3_f32 v0, v0, v87, v88
	v_max3_f32 v250, v250, v71, v72
	v_max3_f32 v0, v0, v89, v90
	v_mfma_f32_32x32x16_bf16 v[18:33], v[220:223], v[118:121], v[18:33]
	v_max3_f32 v250, v250, v73, v74
	v_max3_f32 v0, v0, v91, v92
	v_max3_f32 v250, v250, v75, v76
	v_max3_f32 v0, v0, v93, v94
	v_max3_f32 v250, v250, v77, v78
	v_mfma_f32_32x32x16_bf16 v[2:17], v[224:227], v[118:121], v[2:17]
	v_max3_f32 v0, v0, v95, v96
	v_max3_f32 v250, v250, v79, v80
	v_max_f32_e32 v0, v0, v97
	v_max_f32_e32 v250, v250, v81
	v_max_f32_e32 v0, v0, v250
	v_mul_f32_e32 v0, 0x3e38aa3b, v0
	v_mov_b32_e32 v118, v0
	s_nop 1
	v_permlane32_swap_b32_e32 v0, v118
	v_max_f32_e32 v0, v0, v118
	v_add_f32_e32 v118, 0x41000000, v153
	v_cmp_le_f32_e32 vcc, v0, v118
	s_cmp_lg_u64 vcc, exec
	s_cselect_b64 s[4:5], -1, 0
	v_max_f32_e32 v0, v153, v0
	v_cndmask_b32_e64 v154, v153, v0, s[4:5]
	v_sub_f32_e32 v0, v153, v154
	v_exp_f32_e32 v140, v0
	v_fma_f32 v0, v82, s64, -v154
	v_exp_f32_e32 v122, v0
	v_fma_f32 v0, v83, s64, -v154
	v_exp_f32_e32 v124, v0
	v_fma_f32 v0, v84, s64, -v154
	v_exp_f32_e32 v126, v0
	v_fma_f32 v0, v85, s64, -v154
	v_exp_f32_e32 v128, v0
	v_fma_f32 v0, v86, s64, -v154
	v_exp_f32_e32 v156, v0
	v_fma_f32 v0, v87, s64, -v154
	v_exp_f32_e32 v192, v0
	v_fma_f32 v0, v88, s64, -v154
	v_exp_f32_e32 v194, v0
	v_fma_f32 v0, v89, s64, -v154
	v_exp_f32_e32 v196, v0
	v_fma_f32 v0, v90, s64, -v154
	v_exp_f32_e32 v123, v0
	v_mfma_f32_32x32x16_bf16 v[50:65], v[228:231], v[114:117], v[50:65]
	v_fma_f32 v0, v91, s64, -v154
	v_exp_f32_e32 v125, v0
	v_fma_f32 v0, v92, s64, -v154
	v_exp_f32_e32 v127, v0
	v_fma_f32 v0, v93, s64, -v154
	v_exp_f32_e32 v129, v0
	v_fma_f32 v0, v94, s64, -v154
	v_exp_f32_e32 v157, v0
	v_fma_f32 v0, v95, s64, -v154
	v_exp_f32_e32 v193, v0
	v_fma_f32 v0, v96, s64, -v154
	v_exp_f32_e32 v195, v0
	v_fma_f32 v0, v97, s64, -v154
	v_exp_f32_e32 v197, v0
	v_fma_f32 v0, v66, s64, -v154
	v_exp_f32_e32 v83, v0
	v_fma_f32 v0, v67, s64, -v154
	v_exp_f32_e32 v67, v0
	v_mfma_f32_32x32x16_bf16 v[34:49], v[232:235], v[114:117], v[34:49]
	v_fma_f32 v0, v68, s64, -v154
	v_exp_f32_e32 v85, v0
	v_fma_f32 v0, v69, s64, -v154
	v_exp_f32_e32 v69, v0
	v_fma_f32 v0, v70, s64, -v154
	v_exp_f32_e32 v87, v0
	v_fma_f32 v0, v71, s64, -v154
	v_exp_f32_e32 v71, v0
	v_fma_f32 v0, v72, s64, -v154
	v_exp_f32_e32 v89, v0
	v_fma_f32 v0, v73, s64, -v154
	v_exp_f32_e32 v73, v0
	v_fma_f32 v0, v74, s64, -v154
	v_exp_f32_e32 v82, v0
	v_fma_f32 v0, v75, s64, -v154
	v_exp_f32_e32 v66, v0
	v_fma_f32 v0, v76, s64, -v154
	v_exp_f32_e32 v84, v0
	v_mfma_f32_32x32x16_bf16 v[18:33], v[236:239], v[114:117], v[18:33]
	v_fma_f32 v0, v77, s64, -v154
	v_exp_f32_e32 v68, v0
	v_fma_f32 v0, v78, s64, -v154
	v_exp_f32_e32 v86, v0
	v_fma_f32 v0, v79, s64, -v154
	v_exp_f32_e32 v70, v0
	v_fma_f32 v0, v80, s64, -v154
	v_exp_f32_e32 v88, v0
	v_fma_f32 v0, v81, s64, -v154
	v_exp_f32_e32 v72, v0
	v_mfma_f32_32x32x16_bf16 v[2:17], v[240:243], v[114:117], v[2:17]
	v_cvt_pk_bf16_f32 v118, v83, v67
	v_cvt_pk_bf16_f32 v114, v82, v66
	v_add_f32_e64 v66, v66, v82
	v_add_f32_e64 v67, v67, v83
	v_cvt_pk_bf16_f32 v119, v85, v69
	v_pk_add_f32 v[66:67], v[84:85], v[66:67]
	v_cvt_pk_bf16_f32 v120, v87, v71
	v_pk_add_f32 v[66:67], v[68:69], v[66:67]
	v_cvt_pk_bf16_f32 v121, v89, v73
	v_pk_add_f32 v[66:67], v[86:87], v[66:67]
	v_cvt_pk_bf16_f32 v115, v84, v68
	v_pk_add_f32 v[66:67], v[70:71], v[66:67]
	v_cvt_pk_bf16_f32 v116, v86, v70
	v_pk_add_f32 v[66:67], v[88:89], v[66:67]
	v_cvt_pk_bf16_f32 v117, v88, v72
	v_pk_add_f32 v[90:91], v[72:73], v[66:67]
	v_add_u32_e32 v0, s15, v150
	v_pk_add_f32 v[92:93], v[124:125], v[122:123]
	ds_read_b128 v[86:89], v0 offset:16384
	ds_read_b128 v[82:85], v0 offset:20480
	v_pk_add_f32 v[92:93], v[126:127], v[92:93]
	ds_read_b128 v[78:81], v0 offset:24576
	ds_read_b128 v[74:77], v0 offset:28672
	v_pk_add_f32 v[92:93], v[128:129], v[92:93]
	v_cvt_pk_bf16_f32 v66, v122, v124
	v_pk_add_f32 v[92:93], v[156:157], v[92:93]
	v_cvt_pk_bf16_f32 v67, v126, v128
	v_pk_add_f32 v[92:93], v[192:193], v[92:93]
	v_cvt_pk_bf16_f32 v70, v123, v125
	v_pk_add_f32 v[92:93], v[194:195], v[92:93]
	v_cvt_pk_bf16_f32 v71, v127, v129
	v_pk_add_f32 v[92:93], v[196:197], v[92:93]
	s_add_i32 s11, s11, 1
	v_add_f32_e32 v0, v92, v93
	v_add_f32_e32 v0, v91, v0
	v_add_f32_e32 v0, v90, v0
	v_add_u32_e32 v90, s15, v151
	ds_read_b128 v[126:129], v90 offset:16384
	ds_read_b128 v[122:125], v90 offset:20480
	ds_read_b128 v[94:97], v90 offset:24576
	ds_read_b128 v[90:93], v90 offset:28672
	s_add_i32 s10, s10, 64
	v_cvt_pk_bf16_f32 v68, v156, v192
	v_cvt_pk_bf16_f32 v69, v194, v196
	v_cvt_pk_bf16_f32 v72, v157, v193
	v_cvt_pk_bf16_f32 v73, v195, v197
	v_fma_f32 v152, v152, v140, v0
	s_cmpk_eq_i32 s11, 0x83
	v_lshl_add_u64 v[138:139], v[138:139], 0, s[46:47]
	s_cbranch_scc1 .LBB0_479
	v_mov_b32_e32 v153, v154
	s_mov_b32 s17, s16
	s_branch .LBB0_471
